# v44 + SwiGLU epilogue stores: per-lane 32-bit offset + SALU-advanced scalar base instead of a 64-bit VALU address chain per store
# speedup vs baseline: 1.0076x; 1.0009x over previous
.LBB0_502:
	s_lshl_b32 s42, s53, 10
	v_mov_b32_e32 v161, v154
	v_mov_b32_e32 v165, v155
	s_add_i32 s42, s71, s42
	v_pk_mul_f32 v[122:123], v[122:123], v[126:127]
	v_lshl_add_u32 v148, v161, 2, s42
	ds_read2_b32 v[162:163], v148 offset1:16
	v_pk_mul_f32 v[124:125], v[124:125], v[128:129]
	ds_read2_b32 v[152:153], v148 offset0:32 offset1:48
	ds_read2_b32 v[150:151], v148 offset0:128 offset1:144
	ds_read2_b32 v[148:149], v148 offset0:160 offset1:176
	v_pk_mul_f32 v[114:115], v[114:115], v[118:119]
	v_pk_mul_f32 v[116:117], v[116:117], v[120:121]
	s_waitcnt lgkmcnt(0)
	v_fmamk_f32 v162, v162, 0x3a800000, v160
	v_rsq_f32_e32 v164, v162
	s_lshl_b32 s11, s52, 8
	s_lshl_b32 s13, s54, 7
	v_pk_mul_f32 v[108:109], v[108:109], v[112:113]
	v_mul_f32_e32 v164, 0xbfb8aa3b, v164
	v_pk_mul_f32 v[168:169], v[126:127], v[164:165] op_sel_hi:[1,0]
	v_pk_mul_f32 v[126:127], v[120:121], v[164:165] op_sel_hi:[1,0]
	v_exp_f32_e32 v168, v168
	v_exp_f32_e32 v169, v169
	v_pk_mul_f32 v[166:167], v[128:129], v[164:165] op_sel_hi:[1,0]
	v_pk_mul_f32 v[128:129], v[118:119], v[164:165] op_sel_hi:[1,0]
	v_exp_f32_e32 v126, v126
	v_pk_fma_f32 v[168:169], v[162:163], v[168:169], v[162:163] op_sel_hi:[0,1,0]
	v_rcp_f32_e32 v168, v168
	v_rcp_f32_e32 v169, v169
	v_exp_f32_e32 v127, v127
	v_exp_f32_e32 v128, v128
	v_exp_f32_e32 v129, v129
	v_exp_f32_e32 v166, v166
	v_exp_f32_e32 v167, v167
	v_pk_mul_f32 v[122:123], v[122:123], v[168:169]
	v_pk_fma_f32 v[126:127], v[162:163], v[126:127], v[162:163] op_sel_hi:[0,1,0]
	v_cvt_pk_bf16_f32 v118, v122, v123
	v_fmamk_f32 v122, v163, 0x3a800000, v160
	v_pk_fma_f32 v[128:129], v[162:163], v[128:129], v[162:163] op_sel_hi:[0,1,0]
	v_rcp_f32_e32 v126, v126
	v_rcp_f32_e32 v127, v127
	v_rsq_f32_e32 v123, v122
	v_rcp_f32_e32 v128, v128
	v_rcp_f32_e32 v129, v129
	v_pk_fma_f32 v[166:167], v[162:163], v[166:167], v[162:163] op_sel_hi:[0,1,0]
	v_rcp_f32_e32 v166, v166
	v_rcp_f32_e32 v167, v167
	v_pk_mul_f32 v[116:117], v[116:117], v[126:127]
	v_mul_f32_e32 v126, 0xbfb8aa3b, v123
	v_pk_mul_f32 v[114:115], v[114:115], v[128:129]
	v_pk_mul_f32 v[128:129], v[112:113], v[126:127] op_sel_hi:[1,0]
	v_pk_mul_f32 v[162:163], v[110:111], v[126:127] op_sel_hi:[1,0]
	v_pk_mul_f32 v[106:107], v[106:107], v[110:111]
	v_pk_mul_f32 v[110:111], v[104:105], v[126:127] op_sel_hi:[1,0]
	v_pk_mul_f32 v[112:113], v[102:103], v[126:127] op_sel_hi:[1,0]
	s_or_b32 s52, s13, s68
	s_add_i32 s11, s11, s67
	v_exp_f32_e32 v112, v112
	v_exp_f32_e32 v110, v110
	v_exp_f32_e32 v111, v111
	v_exp_f32_e32 v113, v113
	v_add_u32_e32 v161, s11, v161
	s_ashr_i32 s53, s52, 31
	v_lshlrev_b32_e32 v170, 3, v165
	v_pk_mul_f32 v[124:125], v[124:125], v[166:167]
	v_exp_f32_e32 v162, v162
	v_cvt_pk_bf16_f32 v119, v124, v125
	v_cvt_pk_bf16_f32 v120, v114, v115
	v_exp_f32_e32 v128, v128
	v_exp_f32_e32 v129, v129
	v_exp_f32_e32 v163, v163
	v_cvt_pk_bf16_f32 v121, v116, v117
	s_lshl_b64 s[52:53], s[52:53], 1
	v_lshl_add_u32 v247, v170, 1, s52
	v_mad_u32_u24 v247, v161, s78, v247
	v_pk_fma_f32 v[110:111], v[122:123], v[110:111], v[122:123] op_sel_hi:[0,1,0]
	v_pk_fma_f32 v[112:113], v[122:123], v[112:113], v[122:123] op_sel_hi:[0,1,0]
	global_store_dwordx4 v247, v[118:121], s[88:89]
	v_rcp_f32_e32 v112, v112
	v_rcp_f32_e32 v110, v110
	v_pk_fma_f32 v[118:119], v[122:123], v[128:129], v[122:123] op_sel_hi:[0,1,0]
	v_pk_fma_f32 v[120:121], v[122:123], v[162:163], v[122:123] op_sel_hi:[0,1,0]
	v_rcp_f32_e32 v111, v111
	v_rcp_f32_e32 v113, v113
	v_rcp_f32_e32 v120, v120
	v_rcp_f32_e32 v121, v121
	v_rcp_f32_e32 v118, v118
	v_rcp_f32_e32 v119, v119
	v_pk_mul_f32 v[100:101], v[100:101], v[104:105]
	v_pk_mul_f32 v[98:99], v[98:99], v[102:103]
	v_pk_mul_f32 v[102:103], v[100:101], v[110:111]
	v_pk_mul_f32 v[100:101], v[98:99], v[112:113]
	v_pk_mul_f32 v[108:109], v[108:109], v[118:119]
	v_pk_mul_f32 v[106:107], v[106:107], v[120:121]
	v_pk_mul_f32 v[92:93], v[92:93], v[96:97]
	v_cvt_pk_bf16_f32 v98, v106, v107
	v_cvt_pk_bf16_f32 v99, v108, v109
	v_cvt_pk_bf16_f32 v100, v100, v101
	v_cvt_pk_bf16_f32 v101, v102, v103
	v_fmamk_f32 v102, v152, 0x3a800000, v160
	v_rsq_f32_e32 v103, v102
	v_pk_mul_f32 v[90:91], v[90:91], v[94:95]
	s_mul_i32 s98, s78, 0x10
	s_add_u32 s98, s88, s98
	s_addc_u32 s99, s89, 0
	v_mul_f32_e32 v106, 0xbfb8aa3b, v103
	v_pk_mul_f32 v[108:109], v[96:97], v[106:107] op_sel_hi:[1,0]
	v_pk_mul_f32 v[110:111], v[94:95], v[106:107] op_sel_hi:[1,0]
	v_pk_mul_f32 v[94:95], v[88:89], v[106:107] op_sel_hi:[1,0]
	v_pk_mul_f32 v[96:97], v[86:87], v[106:107] op_sel_hi:[1,0]
	v_exp_f32_e32 v94, v94
	v_exp_f32_e32 v96, v96
	v_exp_f32_e32 v95, v95
	v_exp_f32_e32 v97, v97
	v_exp_f32_e32 v110, v110
	v_exp_f32_e32 v108, v108
	v_exp_f32_e32 v109, v109
	v_exp_f32_e32 v111, v111
	v_pk_fma_f32 v[94:95], v[102:103], v[94:95], v[102:103] op_sel_hi:[0,1,0]
	v_pk_fma_f32 v[96:97], v[102:103], v[96:97], v[102:103] op_sel_hi:[0,1,0]
	global_store_dwordx4 v247, v[98:101], s[98:99]
	v_rcp_f32_e32 v96, v96
	v_rcp_f32_e32 v94, v94
	v_pk_fma_f32 v[98:99], v[102:103], v[108:109], v[102:103] op_sel_hi:[0,1,0]
	v_pk_fma_f32 v[100:101], v[102:103], v[110:111], v[102:103] op_sel_hi:[0,1,0]
	v_rcp_f32_e32 v95, v95
	v_rcp_f32_e32 v97, v97
	v_rcp_f32_e32 v100, v100
	v_rcp_f32_e32 v101, v101
	v_rcp_f32_e32 v98, v98
	v_rcp_f32_e32 v99, v99
	v_pk_mul_f32 v[84:85], v[84:85], v[88:89]
	v_pk_mul_f32 v[82:83], v[82:83], v[86:87]
	v_pk_mul_f32 v[86:87], v[84:85], v[94:95]
	v_pk_mul_f32 v[84:85], v[82:83], v[96:97]
	v_pk_mul_f32 v[92:93], v[92:93], v[98:99]
	v_pk_mul_f32 v[90:91], v[90:91], v[100:101]
	v_pk_mul_f32 v[76:77], v[76:77], v[80:81]
	v_cvt_pk_bf16_f32 v82, v90, v91
	v_cvt_pk_bf16_f32 v83, v92, v93
	v_cvt_pk_bf16_f32 v84, v84, v85
	v_cvt_pk_bf16_f32 v85, v86, v87
	v_fmamk_f32 v86, v153, 0x3a800000, v160
	v_rsq_f32_e32 v87, v86
	v_pk_mul_f32 v[74:75], v[74:75], v[78:79]
	s_mul_i32 s98, s78, 0x20
	s_add_u32 s98, s88, s98
	s_addc_u32 s99, s89, 0
	v_mul_f32_e32 v90, 0xbfb8aa3b, v87
	v_pk_mul_f32 v[92:93], v[80:81], v[90:91] op_sel_hi:[1,0]
	v_pk_mul_f32 v[94:95], v[78:79], v[90:91] op_sel_hi:[1,0]
	v_pk_mul_f32 v[78:79], v[72:73], v[90:91] op_sel_hi:[1,0]
	v_pk_mul_f32 v[80:81], v[70:71], v[90:91] op_sel_hi:[1,0]
	v_exp_f32_e32 v78, v78
	v_exp_f32_e32 v80, v80
	v_exp_f32_e32 v79, v79
	v_exp_f32_e32 v81, v81
	v_exp_f32_e32 v94, v94
	v_exp_f32_e32 v92, v92
	v_exp_f32_e32 v93, v93
	v_exp_f32_e32 v95, v95
	v_pk_fma_f32 v[78:79], v[86:87], v[78:79], v[86:87] op_sel_hi:[0,1,0]
	v_pk_fma_f32 v[80:81], v[86:87], v[80:81], v[86:87] op_sel_hi:[0,1,0]
	global_store_dwordx4 v247, v[82:85], s[98:99]
	v_rcp_f32_e32 v80, v80
	v_rcp_f32_e32 v78, v78
	v_pk_fma_f32 v[82:83], v[86:87], v[92:93], v[86:87] op_sel_hi:[0,1,0]
	v_pk_fma_f32 v[84:85], v[86:87], v[94:95], v[86:87] op_sel_hi:[0,1,0]
	v_rcp_f32_e32 v79, v79
	v_rcp_f32_e32 v81, v81
	v_rcp_f32_e32 v84, v84
	v_rcp_f32_e32 v85, v85
	v_rcp_f32_e32 v82, v82
	v_rcp_f32_e32 v83, v83
	v_pk_mul_f32 v[68:69], v[68:69], v[72:73]
	v_pk_mul_f32 v[66:67], v[66:67], v[70:71]
	v_pk_mul_f32 v[70:71], v[68:69], v[78:79]
	v_pk_mul_f32 v[68:69], v[66:67], v[80:81]
	v_pk_mul_f32 v[76:77], v[76:77], v[82:83]
	v_pk_mul_f32 v[74:75], v[74:75], v[84:85]
	v_pk_mul_f32 v[60:61], v[60:61], v[64:65]
	v_cvt_pk_bf16_f32 v66, v74, v75
	v_cvt_pk_bf16_f32 v67, v76, v77
	v_cvt_pk_bf16_f32 v68, v68, v69
	v_cvt_pk_bf16_f32 v69, v70, v71
	v_fmamk_f32 v70, v150, 0x3a800000, v160
	v_rsq_f32_e32 v71, v70
	v_pk_mul_f32 v[58:59], v[58:59], v[62:63]
	s_mul_i32 s98, s78, 0x30
	s_add_u32 s98, s88, s98
	s_addc_u32 s99, s89, 0
	v_mul_f32_e32 v74, 0xbfb8aa3b, v71
	v_pk_mul_f32 v[76:77], v[64:65], v[74:75] op_sel_hi:[1,0]
	v_pk_mul_f32 v[78:79], v[62:63], v[74:75] op_sel_hi:[1,0]
	v_pk_mul_f32 v[62:63], v[56:57], v[74:75] op_sel_hi:[1,0]
	v_pk_mul_f32 v[64:65], v[54:55], v[74:75] op_sel_hi:[1,0]
	v_exp_f32_e32 v62, v62
	v_exp_f32_e32 v64, v64
	v_exp_f32_e32 v63, v63
	v_exp_f32_e32 v65, v65
	v_exp_f32_e32 v78, v78
	v_exp_f32_e32 v76, v76
	v_exp_f32_e32 v77, v77
	v_exp_f32_e32 v79, v79
	v_pk_fma_f32 v[62:63], v[70:71], v[62:63], v[70:71] op_sel_hi:[0,1,0]
	v_pk_fma_f32 v[64:65], v[70:71], v[64:65], v[70:71] op_sel_hi:[0,1,0]
	global_store_dwordx4 v247, v[66:69], s[98:99]
	v_rcp_f32_e32 v64, v64
	v_rcp_f32_e32 v62, v62
	v_pk_fma_f32 v[66:67], v[70:71], v[76:77], v[70:71] op_sel_hi:[0,1,0]
	v_pk_fma_f32 v[68:69], v[70:71], v[78:79], v[70:71] op_sel_hi:[0,1,0]
	v_rcp_f32_e32 v63, v63
	v_rcp_f32_e32 v65, v65
	v_rcp_f32_e32 v68, v68
	v_rcp_f32_e32 v69, v69
	v_rcp_f32_e32 v66, v66
	v_rcp_f32_e32 v67, v67
	v_pk_mul_f32 v[52:53], v[52:53], v[56:57]
	v_pk_mul_f32 v[50:51], v[50:51], v[54:55]
	v_pk_mul_f32 v[54:55], v[52:53], v[62:63]
	v_pk_mul_f32 v[52:53], v[50:51], v[64:65]
	v_pk_mul_f32 v[60:61], v[60:61], v[66:67]
	v_pk_mul_f32 v[58:59], v[58:59], v[68:69]
	v_pk_mul_f32 v[44:45], v[44:45], v[48:49]
	v_cvt_pk_bf16_f32 v50, v58, v59
	v_cvt_pk_bf16_f32 v51, v60, v61
	v_cvt_pk_bf16_f32 v52, v52, v53
	v_cvt_pk_bf16_f32 v53, v54, v55
	v_fmamk_f32 v54, v151, 0x3a800000, v160
	v_rsq_f32_e32 v55, v54
	v_pk_mul_f32 v[42:43], v[42:43], v[46:47]
	s_mul_i32 s98, s78, 0x80
	s_add_u32 s98, s88, s98
	s_addc_u32 s99, s89, 0
	v_mul_f32_e32 v58, 0xbfb8aa3b, v55
	v_pk_mul_f32 v[60:61], v[48:49], v[58:59] op_sel_hi:[1,0]
	v_pk_mul_f32 v[62:63], v[46:47], v[58:59] op_sel_hi:[1,0]
	v_pk_mul_f32 v[46:47], v[40:41], v[58:59] op_sel_hi:[1,0]
	v_pk_mul_f32 v[48:49], v[38:39], v[58:59] op_sel_hi:[1,0]
	v_exp_f32_e32 v46, v46
	v_exp_f32_e32 v48, v48
	v_exp_f32_e32 v47, v47
	v_exp_f32_e32 v49, v49
	v_exp_f32_e32 v62, v62
	v_exp_f32_e32 v60, v60
	v_exp_f32_e32 v61, v61
	v_exp_f32_e32 v63, v63
	v_pk_fma_f32 v[46:47], v[54:55], v[46:47], v[54:55] op_sel_hi:[0,1,0]
	v_pk_fma_f32 v[48:49], v[54:55], v[48:49], v[54:55] op_sel_hi:[0,1,0]
	global_store_dwordx4 v247, v[50:53], s[98:99]
	v_rcp_f32_e32 v48, v48
	v_rcp_f32_e32 v46, v46
	v_pk_fma_f32 v[50:51], v[54:55], v[60:61], v[54:55] op_sel_hi:[0,1,0]
	v_pk_fma_f32 v[52:53], v[54:55], v[62:63], v[54:55] op_sel_hi:[0,1,0]
	v_rcp_f32_e32 v47, v47
	v_rcp_f32_e32 v49, v49
	v_rcp_f32_e32 v52, v52
	v_rcp_f32_e32 v53, v53
	v_rcp_f32_e32 v50, v50
	v_rcp_f32_e32 v51, v51
	v_pk_mul_f32 v[36:37], v[36:37], v[40:41]
	v_pk_mul_f32 v[34:35], v[34:35], v[38:39]
	v_pk_mul_f32 v[38:39], v[36:37], v[46:47]
	v_pk_mul_f32 v[36:37], v[34:35], v[48:49]
	v_pk_mul_f32 v[44:45], v[44:45], v[50:51]
	v_pk_mul_f32 v[42:43], v[42:43], v[52:53]
	v_pk_mul_f32 v[28:29], v[28:29], v[32:33]
	v_cvt_pk_bf16_f32 v34, v42, v43
	v_cvt_pk_bf16_f32 v35, v44, v45
	v_cvt_pk_bf16_f32 v36, v36, v37
	v_cvt_pk_bf16_f32 v37, v38, v39
	v_fmamk_f32 v38, v148, 0x3a800000, v160
	v_rsq_f32_e32 v39, v38
	v_pk_mul_f32 v[26:27], v[26:27], v[30:31]
	s_mul_i32 s98, s78, 0x90
	s_add_u32 s98, s88, s98
	s_addc_u32 s99, s89, 0
	v_mul_f32_e32 v42, 0xbfb8aa3b, v39
	v_pk_mul_f32 v[44:45], v[32:33], v[42:43] op_sel_hi:[1,0]
	v_pk_mul_f32 v[46:47], v[30:31], v[42:43] op_sel_hi:[1,0]
	v_pk_mul_f32 v[30:31], v[24:25], v[42:43] op_sel_hi:[1,0]
	v_pk_mul_f32 v[32:33], v[22:23], v[42:43] op_sel_hi:[1,0]
	v_exp_f32_e32 v30, v30
	v_exp_f32_e32 v32, v32
	v_exp_f32_e32 v31, v31
	v_exp_f32_e32 v33, v33
	v_exp_f32_e32 v46, v46
	v_exp_f32_e32 v44, v44
	v_exp_f32_e32 v45, v45
	v_exp_f32_e32 v47, v47
	v_pk_fma_f32 v[30:31], v[38:39], v[30:31], v[38:39] op_sel_hi:[0,1,0]
	v_pk_fma_f32 v[32:33], v[38:39], v[32:33], v[38:39] op_sel_hi:[0,1,0]
	global_store_dwordx4 v247, v[34:37], s[98:99]
	v_rcp_f32_e32 v32, v32
	v_rcp_f32_e32 v30, v30
	v_pk_fma_f32 v[34:35], v[38:39], v[44:45], v[38:39] op_sel_hi:[0,1,0]
	v_pk_fma_f32 v[36:37], v[38:39], v[46:47], v[38:39] op_sel_hi:[0,1,0]
	v_rcp_f32_e32 v31, v31
	v_rcp_f32_e32 v33, v33
	v_rcp_f32_e32 v36, v36
	v_rcp_f32_e32 v37, v37
	v_rcp_f32_e32 v34, v34
	v_rcp_f32_e32 v35, v35
	v_pk_mul_f32 v[20:21], v[20:21], v[24:25]
	v_pk_mul_f32 v[18:19], v[18:19], v[22:23]
	v_pk_mul_f32 v[22:23], v[20:21], v[30:31]
	v_pk_mul_f32 v[20:21], v[18:19], v[32:33]
	v_pk_mul_f32 v[28:29], v[28:29], v[34:35]
	v_pk_mul_f32 v[26:27], v[26:27], v[36:37]
	v_pk_mul_f32 v[12:13], v[12:13], v[16:17]
	v_cvt_pk_bf16_f32 v18, v26, v27
	v_cvt_pk_bf16_f32 v19, v28, v29
	v_cvt_pk_bf16_f32 v20, v20, v21
	v_cvt_pk_bf16_f32 v21, v22, v23
	v_fmamk_f32 v22, v149, 0x3a800000, v160
	v_rsq_f32_e32 v23, v22
	v_pk_mul_f32 v[10:11], v[10:11], v[14:15]
	s_mul_i32 s98, s78, 0xa0
	s_add_u32 s98, s88, s98
	s_addc_u32 s99, s89, 0
	v_mul_f32_e32 v26, 0xbfb8aa3b, v23
	v_pk_mul_f32 v[28:29], v[16:17], v[26:27] op_sel_hi:[1,0]
	v_pk_mul_f32 v[30:31], v[14:15], v[26:27] op_sel_hi:[1,0]
	v_pk_mul_f32 v[14:15], v[8:9], v[26:27] op_sel_hi:[1,0]
	v_pk_mul_f32 v[16:17], v[6:7], v[26:27] op_sel_hi:[1,0]
	v_exp_f32_e32 v14, v14
	v_exp_f32_e32 v16, v16
	v_exp_f32_e32 v15, v15
	v_exp_f32_e32 v17, v17
	v_exp_f32_e32 v30, v30
	v_exp_f32_e32 v28, v28
	v_exp_f32_e32 v29, v29
	v_exp_f32_e32 v31, v31
	v_pk_fma_f32 v[14:15], v[22:23], v[14:15], v[22:23] op_sel_hi:[0,1,0]
	v_pk_fma_f32 v[16:17], v[22:23], v[16:17], v[22:23] op_sel_hi:[0,1,0]
	global_store_dwordx4 v247, v[18:21], s[98:99]
	v_rcp_f32_e32 v16, v16
	v_rcp_f32_e32 v14, v14
	v_pk_fma_f32 v[18:19], v[22:23], v[28:29], v[22:23] op_sel_hi:[0,1,0]
	v_pk_fma_f32 v[20:21], v[22:23], v[30:31], v[22:23] op_sel_hi:[0,1,0]
	v_rcp_f32_e32 v15, v15
	v_rcp_f32_e32 v17, v17
	v_rcp_f32_e32 v20, v20
	v_rcp_f32_e32 v21, v21
	v_rcp_f32_e32 v18, v18
	v_rcp_f32_e32 v19, v19
	v_pk_mul_f32 v[4:5], v[4:5], v[8:9]
	v_pk_mul_f32 v[2:3], v[2:3], v[6:7]
	v_pk_mul_f32 v[6:7], v[4:5], v[14:15]
	v_pk_mul_f32 v[4:5], v[2:3], v[16:17]
	v_pk_mul_f32 v[12:13], v[12:13], v[18:19]
	v_pk_mul_f32 v[10:11], v[10:11], v[20:21]
	s_andn2_b64 vcc, exec, s[6:7]
	v_cvt_pk_bf16_f32 v2, v10, v11
	v_cvt_pk_bf16_f32 v3, v12, v13
	v_cvt_pk_bf16_f32 v4, v4, v5
	v_cvt_pk_bf16_f32 v5, v6, v7
	s_mul_i32 s98, s78, 0xb0
	s_add_u32 s98, s88, s98
	s_addc_u32 s99, s89, 0
	s_mov_b64 s[6:7], -1
	global_store_dwordx4 v247, v[2:5], s[98:99]
	s_cbranch_vccnz .LBB0_492
	s_andn2_b64 vcc, exec, s[0:1]
	s_cbranch_vccnz .LBB0_491
	s_barrier
	s_branch .LBB0_491

.LBB0_1727:
	s_lshl_b32 s5, s18, 8
	s_lshl_b32 s18, s19, 10
	v_mov_b32_e32 v163, v1
	v_mov_b32_e32 v165, v154
	s_add_i32 s18, s47, s18
	v_pk_mul_f32 v[122:123], v[122:123], v[126:127]
	v_lshl_add_u32 v148, v163, 2, s18
	ds_read2_b32 v[160:161], v148 offset1:16
	v_pk_mul_f32 v[124:125], v[124:125], v[128:129]
	ds_read2_b32 v[152:153], v148 offset0:32 offset1:48
	ds_read2_b32 v[150:151], v148 offset0:128 offset1:144
	ds_read2_b32 v[148:149], v148 offset0:160 offset1:176
	v_pk_mul_f32 v[114:115], v[114:115], v[118:119]
	v_pk_mul_f32 v[116:117], v[116:117], v[120:121]
	s_waitcnt lgkmcnt(0)
	v_fmamk_f32 v162, v160, 0x3a800000, v159
	v_rsq_f32_e32 v164, v162
	s_add_i32 s5, s5, s42
	s_lshl_b32 s13, s20, 7
	v_add_u32_e32 v160, s5, v163
	v_mul_f32_e32 v164, 0xbfb8aa3b, v164
	v_pk_mul_f32 v[168:169], v[126:127], v[164:165] op_sel_hi:[1,0]
	v_pk_mul_f32 v[126:127], v[120:121], v[164:165] op_sel_hi:[1,0]
	v_exp_f32_e32 v168, v168
	v_exp_f32_e32 v169, v169
	v_pk_mul_f32 v[166:167], v[128:129], v[164:165] op_sel_hi:[1,0]
	v_pk_mul_f32 v[128:129], v[118:119], v[164:165] op_sel_hi:[1,0]
	v_exp_f32_e32 v126, v126
	v_pk_fma_f32 v[168:169], v[162:163], v[168:169], v[162:163] op_sel_hi:[0,1,0]
	v_rcp_f32_e32 v168, v168
	v_rcp_f32_e32 v169, v169
	v_exp_f32_e32 v127, v127
	v_exp_f32_e32 v128, v128
	v_exp_f32_e32 v129, v129
	v_exp_f32_e32 v166, v166
	v_exp_f32_e32 v167, v167
	v_pk_mul_f32 v[122:123], v[122:123], v[168:169]
	v_pk_fma_f32 v[126:127], v[162:163], v[126:127], v[162:163] op_sel_hi:[0,1,0]
	v_cvt_pk_bf16_f32 v118, v122, v123
	v_fmamk_f32 v122, v161, 0x3a800000, v159
	v_pk_fma_f32 v[128:129], v[162:163], v[128:129], v[162:163] op_sel_hi:[0,1,0]
	v_rcp_f32_e32 v126, v126
	v_rcp_f32_e32 v127, v127
	v_rsq_f32_e32 v123, v122
	v_rcp_f32_e32 v128, v128
	v_rcp_f32_e32 v129, v129
	v_pk_fma_f32 v[166:167], v[162:163], v[166:167], v[162:163] op_sel_hi:[0,1,0]
	v_rcp_f32_e32 v166, v166
	v_rcp_f32_e32 v167, v167
	v_pk_mul_f32 v[116:117], v[116:117], v[126:127]
	v_mul_f32_e32 v126, 0xbfb8aa3b, v123
	v_pk_mul_f32 v[114:115], v[114:115], v[128:129]
	v_pk_mul_f32 v[128:129], v[112:113], v[126:127] op_sel_hi:[1,0]
	v_pk_mul_f32 v[162:163], v[110:111], v[126:127] op_sel_hi:[1,0]
	v_pk_mul_f32 v[108:109], v[108:109], v[112:113]
	v_pk_mul_f32 v[106:107], v[106:107], v[110:111]
	v_pk_mul_f32 v[110:111], v[104:105], v[126:127] op_sel_hi:[1,0]
	v_pk_mul_f32 v[112:113], v[102:103], v[126:127] op_sel_hi:[1,0]
	s_or_b32 s18, s13, s43
	v_exp_f32_e32 v112, v112
	v_exp_f32_e32 v110, v110
	v_exp_f32_e32 v111, v111
	v_exp_f32_e32 v113, v113
	s_ashr_i32 s19, s18, 31
	v_lshlrev_b32_e32 v170, 3, v165
	v_pk_mul_f32 v[124:125], v[124:125], v[166:167]
	v_exp_f32_e32 v162, v162
	v_cvt_pk_bf16_f32 v119, v124, v125
	v_cvt_pk_bf16_f32 v120, v114, v115
	v_exp_f32_e32 v128, v128
	v_exp_f32_e32 v129, v129
	v_exp_f32_e32 v163, v163
	v_cvt_pk_bf16_f32 v121, v116, v117
	s_lshl_b64 s[18:19], s[18:19], 1
	v_lshl_add_u32 v247, v170, 1, s18
	v_mad_u32_u24 v247, v160, s55, v247
	v_pk_fma_f32 v[110:111], v[122:123], v[110:111], v[122:123] op_sel_hi:[0,1,0]
	v_pk_fma_f32 v[112:113], v[122:123], v[112:113], v[122:123] op_sel_hi:[0,1,0]
	global_store_dwordx4 v247, v[118:121], s[70:71]
	v_rcp_f32_e32 v112, v112
	v_rcp_f32_e32 v110, v110
	v_pk_fma_f32 v[118:119], v[122:123], v[128:129], v[122:123] op_sel_hi:[0,1,0]
	v_pk_fma_f32 v[120:121], v[122:123], v[162:163], v[122:123] op_sel_hi:[0,1,0]
	v_rcp_f32_e32 v111, v111
	v_rcp_f32_e32 v113, v113
	v_rcp_f32_e32 v120, v120
	v_rcp_f32_e32 v121, v121
	v_rcp_f32_e32 v118, v118
	v_rcp_f32_e32 v119, v119
	v_pk_mul_f32 v[100:101], v[100:101], v[104:105]
	v_pk_mul_f32 v[98:99], v[98:99], v[102:103]
	v_pk_mul_f32 v[102:103], v[100:101], v[110:111]
	v_pk_mul_f32 v[100:101], v[98:99], v[112:113]
	v_pk_mul_f32 v[108:109], v[108:109], v[118:119]
	v_pk_mul_f32 v[106:107], v[106:107], v[120:121]
	v_pk_mul_f32 v[92:93], v[92:93], v[96:97]
	v_cvt_pk_bf16_f32 v98, v106, v107
	v_cvt_pk_bf16_f32 v99, v108, v109
	v_cvt_pk_bf16_f32 v100, v100, v101
	v_cvt_pk_bf16_f32 v101, v102, v103
	v_fmamk_f32 v102, v152, 0x3a800000, v159
	v_rsq_f32_e32 v103, v102
	v_pk_mul_f32 v[90:91], v[90:91], v[94:95]
	s_mul_i32 s98, s55, 0x10
	s_add_u32 s98, s70, s98
	s_addc_u32 s99, s71, 0
	v_mul_f32_e32 v106, 0xbfb8aa3b, v103
	v_pk_mul_f32 v[108:109], v[96:97], v[106:107] op_sel_hi:[1,0]
	v_pk_mul_f32 v[110:111], v[94:95], v[106:107] op_sel_hi:[1,0]
	v_pk_mul_f32 v[94:95], v[88:89], v[106:107] op_sel_hi:[1,0]
	v_pk_mul_f32 v[96:97], v[86:87], v[106:107] op_sel_hi:[1,0]
	v_exp_f32_e32 v94, v94
	v_exp_f32_e32 v96, v96
	v_exp_f32_e32 v95, v95
	v_exp_f32_e32 v97, v97
	v_exp_f32_e32 v110, v110
	v_exp_f32_e32 v108, v108
	v_exp_f32_e32 v109, v109
	v_exp_f32_e32 v111, v111
	v_pk_fma_f32 v[94:95], v[102:103], v[94:95], v[102:103] op_sel_hi:[0,1,0]
	v_pk_fma_f32 v[96:97], v[102:103], v[96:97], v[102:103] op_sel_hi:[0,1,0]
	global_store_dwordx4 v247, v[98:101], s[98:99]
	v_rcp_f32_e32 v96, v96
	v_rcp_f32_e32 v94, v94
	v_pk_fma_f32 v[98:99], v[102:103], v[108:109], v[102:103] op_sel_hi:[0,1,0]
	v_pk_fma_f32 v[100:101], v[102:103], v[110:111], v[102:103] op_sel_hi:[0,1,0]
	v_rcp_f32_e32 v95, v95
	v_rcp_f32_e32 v97, v97
	v_rcp_f32_e32 v100, v100
	v_rcp_f32_e32 v101, v101
	v_rcp_f32_e32 v98, v98
	v_rcp_f32_e32 v99, v99
	v_pk_mul_f32 v[84:85], v[84:85], v[88:89]
	v_pk_mul_f32 v[82:83], v[82:83], v[86:87]
	v_pk_mul_f32 v[86:87], v[84:85], v[94:95]
	v_pk_mul_f32 v[84:85], v[82:83], v[96:97]
	v_pk_mul_f32 v[92:93], v[92:93], v[98:99]
	v_pk_mul_f32 v[90:91], v[90:91], v[100:101]
	v_pk_mul_f32 v[76:77], v[76:77], v[80:81]
	v_cvt_pk_bf16_f32 v82, v90, v91
	v_cvt_pk_bf16_f32 v83, v92, v93
	v_cvt_pk_bf16_f32 v84, v84, v85
	v_cvt_pk_bf16_f32 v85, v86, v87
	v_fmamk_f32 v86, v153, 0x3a800000, v159
	v_rsq_f32_e32 v87, v86
	v_pk_mul_f32 v[74:75], v[74:75], v[78:79]
	s_mul_i32 s98, s55, 0x20
	s_add_u32 s98, s70, s98
	s_addc_u32 s99, s71, 0
	v_mul_f32_e32 v90, 0xbfb8aa3b, v87
	v_pk_mul_f32 v[92:93], v[80:81], v[90:91] op_sel_hi:[1,0]
	v_pk_mul_f32 v[94:95], v[78:79], v[90:91] op_sel_hi:[1,0]
	v_pk_mul_f32 v[78:79], v[72:73], v[90:91] op_sel_hi:[1,0]
	v_pk_mul_f32 v[80:81], v[70:71], v[90:91] op_sel_hi:[1,0]
	v_exp_f32_e32 v78, v78
	v_exp_f32_e32 v80, v80
	v_exp_f32_e32 v79, v79
	v_exp_f32_e32 v81, v81
	v_exp_f32_e32 v94, v94
	v_exp_f32_e32 v92, v92
	v_exp_f32_e32 v93, v93
	v_exp_f32_e32 v95, v95
	v_pk_fma_f32 v[78:79], v[86:87], v[78:79], v[86:87] op_sel_hi:[0,1,0]
	v_pk_fma_f32 v[80:81], v[86:87], v[80:81], v[86:87] op_sel_hi:[0,1,0]
	global_store_dwordx4 v247, v[82:85], s[98:99]
	v_rcp_f32_e32 v80, v80
	v_rcp_f32_e32 v78, v78
	v_pk_fma_f32 v[82:83], v[86:87], v[92:93], v[86:87] op_sel_hi:[0,1,0]
	v_pk_fma_f32 v[84:85], v[86:87], v[94:95], v[86:87] op_sel_hi:[0,1,0]
	v_rcp_f32_e32 v79, v79
	v_rcp_f32_e32 v81, v81
	v_rcp_f32_e32 v84, v84
	v_rcp_f32_e32 v85, v85
	v_rcp_f32_e32 v82, v82
	v_rcp_f32_e32 v83, v83
	v_pk_mul_f32 v[68:69], v[68:69], v[72:73]
	v_pk_mul_f32 v[66:67], v[66:67], v[70:71]
	v_pk_mul_f32 v[70:71], v[68:69], v[78:79]
	v_pk_mul_f32 v[68:69], v[66:67], v[80:81]
	v_pk_mul_f32 v[76:77], v[76:77], v[82:83]
	v_pk_mul_f32 v[74:75], v[74:75], v[84:85]
	v_pk_mul_f32 v[60:61], v[60:61], v[64:65]
	v_cvt_pk_bf16_f32 v66, v74, v75
	v_cvt_pk_bf16_f32 v67, v76, v77
	v_cvt_pk_bf16_f32 v68, v68, v69
	v_cvt_pk_bf16_f32 v69, v70, v71
	v_fmamk_f32 v70, v150, 0x3a800000, v159
	v_rsq_f32_e32 v71, v70
	v_pk_mul_f32 v[58:59], v[58:59], v[62:63]
	s_mul_i32 s98, s55, 0x30
	s_add_u32 s98, s70, s98
	s_addc_u32 s99, s71, 0
	v_mul_f32_e32 v74, 0xbfb8aa3b, v71
	v_pk_mul_f32 v[76:77], v[64:65], v[74:75] op_sel_hi:[1,0]
	v_pk_mul_f32 v[78:79], v[62:63], v[74:75] op_sel_hi:[1,0]
	v_pk_mul_f32 v[62:63], v[56:57], v[74:75] op_sel_hi:[1,0]
	v_pk_mul_f32 v[64:65], v[54:55], v[74:75] op_sel_hi:[1,0]
	v_exp_f32_e32 v62, v62
	v_exp_f32_e32 v64, v64
	v_exp_f32_e32 v63, v63
	v_exp_f32_e32 v65, v65
	v_exp_f32_e32 v78, v78
	v_exp_f32_e32 v76, v76
	v_exp_f32_e32 v77, v77
	v_exp_f32_e32 v79, v79
	v_pk_fma_f32 v[62:63], v[70:71], v[62:63], v[70:71] op_sel_hi:[0,1,0]
	v_pk_fma_f32 v[64:65], v[70:71], v[64:65], v[70:71] op_sel_hi:[0,1,0]
	global_store_dwordx4 v247, v[66:69], s[98:99]
	v_rcp_f32_e32 v64, v64
	v_rcp_f32_e32 v62, v62
	v_pk_fma_f32 v[66:67], v[70:71], v[76:77], v[70:71] op_sel_hi:[0,1,0]
	v_pk_fma_f32 v[68:69], v[70:71], v[78:79], v[70:71] op_sel_hi:[0,1,0]
	v_rcp_f32_e32 v63, v63
	v_rcp_f32_e32 v65, v65
	v_rcp_f32_e32 v68, v68
	v_rcp_f32_e32 v69, v69
	v_rcp_f32_e32 v66, v66
	v_rcp_f32_e32 v67, v67
	v_pk_mul_f32 v[52:53], v[52:53], v[56:57]
	v_pk_mul_f32 v[50:51], v[50:51], v[54:55]
	v_pk_mul_f32 v[54:55], v[52:53], v[62:63]
	v_pk_mul_f32 v[52:53], v[50:51], v[64:65]
	v_pk_mul_f32 v[60:61], v[60:61], v[66:67]
	v_pk_mul_f32 v[58:59], v[58:59], v[68:69]
	v_pk_mul_f32 v[44:45], v[44:45], v[48:49]
	v_cvt_pk_bf16_f32 v50, v58, v59
	v_cvt_pk_bf16_f32 v51, v60, v61
	v_cvt_pk_bf16_f32 v52, v52, v53
	v_cvt_pk_bf16_f32 v53, v54, v55
	v_fmamk_f32 v54, v151, 0x3a800000, v159
	v_rsq_f32_e32 v55, v54
	v_pk_mul_f32 v[42:43], v[42:43], v[46:47]
	s_mul_i32 s98, s55, 0x80
	s_add_u32 s98, s70, s98
	s_addc_u32 s99, s71, 0
	v_mul_f32_e32 v58, 0xbfb8aa3b, v55
	v_pk_mul_f32 v[60:61], v[48:49], v[58:59] op_sel_hi:[1,0]
	v_pk_mul_f32 v[62:63], v[46:47], v[58:59] op_sel_hi:[1,0]
	v_pk_mul_f32 v[46:47], v[40:41], v[58:59] op_sel_hi:[1,0]
	v_pk_mul_f32 v[48:49], v[38:39], v[58:59] op_sel_hi:[1,0]
	v_exp_f32_e32 v46, v46
	v_exp_f32_e32 v48, v48
	v_exp_f32_e32 v47, v47
	v_exp_f32_e32 v49, v49
	v_exp_f32_e32 v62, v62
	v_exp_f32_e32 v60, v60
	v_exp_f32_e32 v61, v61
	v_exp_f32_e32 v63, v63
	v_pk_fma_f32 v[46:47], v[54:55], v[46:47], v[54:55] op_sel_hi:[0,1,0]
	v_pk_fma_f32 v[48:49], v[54:55], v[48:49], v[54:55] op_sel_hi:[0,1,0]
	global_store_dwordx4 v247, v[50:53], s[98:99]
	v_rcp_f32_e32 v48, v48
	v_rcp_f32_e32 v46, v46
	v_pk_fma_f32 v[50:51], v[54:55], v[60:61], v[54:55] op_sel_hi:[0,1,0]
	v_pk_fma_f32 v[52:53], v[54:55], v[62:63], v[54:55] op_sel_hi:[0,1,0]
	v_rcp_f32_e32 v47, v47
	v_rcp_f32_e32 v49, v49
	v_rcp_f32_e32 v52, v52
	v_rcp_f32_e32 v53, v53
	v_rcp_f32_e32 v50, v50
	v_rcp_f32_e32 v51, v51
	v_pk_mul_f32 v[36:37], v[36:37], v[40:41]
	v_pk_mul_f32 v[34:35], v[34:35], v[38:39]
	v_pk_mul_f32 v[38:39], v[36:37], v[46:47]
	v_pk_mul_f32 v[36:37], v[34:35], v[48:49]
	v_pk_mul_f32 v[44:45], v[44:45], v[50:51]
	v_pk_mul_f32 v[42:43], v[42:43], v[52:53]
	v_pk_mul_f32 v[28:29], v[28:29], v[32:33]
	v_cvt_pk_bf16_f32 v34, v42, v43
	v_cvt_pk_bf16_f32 v35, v44, v45
	v_cvt_pk_bf16_f32 v36, v36, v37
	v_cvt_pk_bf16_f32 v37, v38, v39
	v_fmamk_f32 v38, v148, 0x3a800000, v159
	v_rsq_f32_e32 v39, v38
	v_pk_mul_f32 v[26:27], v[26:27], v[30:31]
	s_mul_i32 s98, s55, 0x90
	s_add_u32 s98, s70, s98
	s_addc_u32 s99, s71, 0
	v_mul_f32_e32 v42, 0xbfb8aa3b, v39
	v_pk_mul_f32 v[44:45], v[32:33], v[42:43] op_sel_hi:[1,0]
	v_pk_mul_f32 v[46:47], v[30:31], v[42:43] op_sel_hi:[1,0]
	v_pk_mul_f32 v[30:31], v[24:25], v[42:43] op_sel_hi:[1,0]
	v_pk_mul_f32 v[32:33], v[22:23], v[42:43] op_sel_hi:[1,0]
	v_exp_f32_e32 v30, v30
	v_exp_f32_e32 v32, v32
	v_exp_f32_e32 v31, v31
	v_exp_f32_e32 v33, v33
	v_exp_f32_e32 v46, v46
	v_exp_f32_e32 v44, v44
	v_exp_f32_e32 v45, v45
	v_exp_f32_e32 v47, v47
	v_pk_fma_f32 v[30:31], v[38:39], v[30:31], v[38:39] op_sel_hi:[0,1,0]
	v_pk_fma_f32 v[32:33], v[38:39], v[32:33], v[38:39] op_sel_hi:[0,1,0]
	global_store_dwordx4 v247, v[34:37], s[98:99]
	v_rcp_f32_e32 v32, v32
	v_rcp_f32_e32 v30, v30
	v_pk_fma_f32 v[34:35], v[38:39], v[44:45], v[38:39] op_sel_hi:[0,1,0]
	v_pk_fma_f32 v[36:37], v[38:39], v[46:47], v[38:39] op_sel_hi:[0,1,0]
	v_rcp_f32_e32 v31, v31
	v_rcp_f32_e32 v33, v33
	v_rcp_f32_e32 v36, v36
	v_rcp_f32_e32 v37, v37
	v_rcp_f32_e32 v34, v34
	v_rcp_f32_e32 v35, v35
	v_pk_mul_f32 v[20:21], v[20:21], v[24:25]
	v_pk_mul_f32 v[18:19], v[18:19], v[22:23]
	v_pk_mul_f32 v[22:23], v[20:21], v[30:31]
	v_pk_mul_f32 v[20:21], v[18:19], v[32:33]
	v_pk_mul_f32 v[28:29], v[28:29], v[34:35]
	v_pk_mul_f32 v[26:27], v[26:27], v[36:37]
	v_pk_mul_f32 v[12:13], v[12:13], v[16:17]
	v_cvt_pk_bf16_f32 v18, v26, v27
	v_cvt_pk_bf16_f32 v19, v28, v29
	v_cvt_pk_bf16_f32 v20, v20, v21
	v_cvt_pk_bf16_f32 v21, v22, v23
	v_fmamk_f32 v22, v149, 0x3a800000, v159
	v_rsq_f32_e32 v23, v22
	v_pk_mul_f32 v[10:11], v[10:11], v[14:15]
	s_mul_i32 s98, s55, 0xa0
	s_add_u32 s98, s70, s98
	s_addc_u32 s99, s71, 0
	v_mul_f32_e32 v26, 0xbfb8aa3b, v23
	v_pk_mul_f32 v[28:29], v[16:17], v[26:27] op_sel_hi:[1,0]
	v_pk_mul_f32 v[30:31], v[14:15], v[26:27] op_sel_hi:[1,0]
	v_pk_mul_f32 v[14:15], v[8:9], v[26:27] op_sel_hi:[1,0]
	v_pk_mul_f32 v[16:17], v[6:7], v[26:27] op_sel_hi:[1,0]
	v_exp_f32_e32 v14, v14
	v_exp_f32_e32 v16, v16
	v_exp_f32_e32 v15, v15
	v_exp_f32_e32 v17, v17
	v_exp_f32_e32 v30, v30
	v_exp_f32_e32 v28, v28
	v_exp_f32_e32 v29, v29
	v_exp_f32_e32 v31, v31
	v_pk_fma_f32 v[14:15], v[22:23], v[14:15], v[22:23] op_sel_hi:[0,1,0]
	v_pk_fma_f32 v[16:17], v[22:23], v[16:17], v[22:23] op_sel_hi:[0,1,0]
	global_store_dwordx4 v247, v[18:21], s[98:99]
	v_rcp_f32_e32 v16, v16
	v_rcp_f32_e32 v14, v14
	v_pk_fma_f32 v[18:19], v[22:23], v[28:29], v[22:23] op_sel_hi:[0,1,0]
	v_pk_fma_f32 v[20:21], v[22:23], v[30:31], v[22:23] op_sel_hi:[0,1,0]
	v_rcp_f32_e32 v15, v15
	v_rcp_f32_e32 v17, v17
	v_rcp_f32_e32 v20, v20
	v_rcp_f32_e32 v21, v21
	v_rcp_f32_e32 v18, v18
	v_rcp_f32_e32 v19, v19
	v_pk_mul_f32 v[4:5], v[4:5], v[8:9]
	v_pk_mul_f32 v[2:3], v[2:3], v[6:7]
	v_pk_mul_f32 v[6:7], v[4:5], v[14:15]
	v_pk_mul_f32 v[4:5], v[2:3], v[16:17]
	v_pk_mul_f32 v[12:13], v[12:13], v[18:19]
	v_pk_mul_f32 v[10:11], v[10:11], v[20:21]
	s_andn2_b64 vcc, exec, s[6:7]
	v_cvt_pk_bf16_f32 v2, v10, v11
	v_cvt_pk_bf16_f32 v3, v12, v13
	v_cvt_pk_bf16_f32 v4, v4, v5
	v_cvt_pk_bf16_f32 v5, v6, v7
	s_mul_i32 s98, s55, 0xb0
	s_add_u32 s98, s70, s98
	s_addc_u32 s99, s71, 0
	s_mov_b64 s[6:7], -1
	global_store_dwordx4 v247, v[2:5], s[98:99]
	s_cbranch_vccnz .LBB0_1717
	s_andn2_b64 vcc, exec, s[0:1]
	s_cbranch_vccnz .LBB0_1716
	s_barrier
	s_branch .LBB0_1716

	.amdhsa_kernel _Z6mk_fwd4Args
		.amdhsa_group_segment_fixed_size 0
		.amdhsa_private_segment_fixed_size 0
		.amdhsa_kernarg_size 472
		.amdhsa_user_sgpr_count 2
		.amdhsa_user_sgpr_dispatch_ptr 0
		.amdhsa_user_sgpr_queue_ptr 0
		.amdhsa_user_sgpr_kernarg_segment_ptr 1
		.amdhsa_user_sgpr_dispatch_id 0
		.amdhsa_user_sgpr_kernarg_preload_length 0
		.amdhsa_user_sgpr_kernarg_preload_offset 0
		.amdhsa_user_sgpr_private_segment_size 0
		.amdhsa_uses_dynamic_stack 0
		.amdhsa_enable_private_segment 0
		.amdhsa_system_sgpr_workgroup_id_x 1
		.amdhsa_system_sgpr_workgroup_id_y 0
		.amdhsa_system_sgpr_workgroup_id_z 0
		.amdhsa_system_sgpr_workgroup_info 0
		.amdhsa_system_vgpr_workitem_id 0
		.amdhsa_next_free_vgpr 248
		.amdhsa_next_free_sgpr 102
		.amdhsa_accum_offset 248
		.amdhsa_reserve_vcc 1
		.amdhsa_float_round_mode_32 0
		.amdhsa_float_round_mode_16_64 0
		.amdhsa_float_denorm_mode_32 3
		.amdhsa_float_denorm_mode_16_64 3
		.amdhsa_dx10_clamp 1
		.amdhsa_ieee_mode 1
		.amdhsa_fp16_overflow 0
		.amdhsa_tg_split 0
		.amdhsa_exception_fp_ieee_invalid_op 0
		.amdhsa_exception_fp_denorm_src 0
		.amdhsa_exception_fp_ieee_div_zero 0
		.amdhsa_exception_fp_ieee_overflow 0
		.amdhsa_exception_fp_ieee_underflow 0
		.amdhsa_exception_fp_ieee_inexact 0
		.amdhsa_exception_int_div_zero 0
	.end_amdhsa_kernel

amdhsa.kernels:
  - .agpr_count:     0
    .args:
      - .offset:         0
        .size:           216
        .value_kind:     by_value
      - .offset:         216
        .size:           4
        .value_kind:     hidden_block_count_x
      - .offset:         220
        .size:           4
        .value_kind:     hidden_block_count_y
      - .offset:         224
        .size:           4
        .value_kind:     hidden_block_count_z
      - .offset:         228
        .size:           2
        .value_kind:     hidden_group_size_x
      - .offset:         230
        .size:           2
        .value_kind:     hidden_group_size_y
      - .offset:         232
        .size:           2
        .value_kind:     hidden_group_size_z
      - .offset:         234
        .size:           2
        .value_kind:     hidden_remainder_x
      - .offset:         236
        .size:           2
        .value_kind:     hidden_remainder_y
      - .offset:         238
        .size:           2
        .value_kind:     hidden_remainder_z
      - .offset:         256
        .size:           8
        .value_kind:     hidden_global_offset_x
      - .offset:         264
        .size:           8
        .value_kind:     hidden_global_offset_y
      - .offset:         272
        .size:           8
        .value_kind:     hidden_global_offset_z
      - .offset:         280
        .size:           2
        .value_kind:     hidden_grid_dims
      - .offset:         336
        .size:           4
        .value_kind:     hidden_dynamic_lds_size
    .group_segment_fixed_size: 0
    .kernarg_segment_align: 8
    .kernarg_segment_size: 472
    .language:       OpenCL C
    .language_version:
      - 2
      - 0
    .max_flat_workgroup_size: 512
    .name:           _Z6mk_fwd4Args
    .private_segment_fixed_size: 0
    .sgpr_count:     108
    .sgpr_spill_count: 66
    .symbol:         _Z6mk_fwd4Args.kd
    .uniform_work_group_size: 1
    .uses_dynamic_stack: false
    .vgpr_count:     248
    .vgpr_spill_count: 0
    .wavefront_size: 64
